# v7 + sample-attention K/V staging: all 10 cache loads issued before one wait (was 5 serialized round trips)
# baseline (speedup 1.0000x reference)
; #define LAS __attribute__((address_space(3)))
; __device__ __forceinline__ float bf2f(unsigned b) { return __uint_as_float(b << 16); }
; __device__ __forceinline__ void attn_sample_item(const Params& P, LAS unsigned char* lds, int l, int db, int kvh, int tid_in) {
;     ...
; #pragma unroll
;     for (int k = 0; k < 5; ++k) {
;         const int e = tid + 512 * k;
;         if (e < 132 * 16) {
;             const int key = e >> 4, d4 = (e & 15) * 4;
;             f32x4 kv, vv;
;             if (key < 128) { kv = *(const f32x4*)(P.in[I_CK] + ((cbase + key) * 2 + kvh) * 64 + d4); vv = *(const f32x4*)(P.in[I_CV] + ((cbase + key) * 2 + kvh) * 64 + d4); }
;             else { kv = *(const f32x4*)(P.out + O_WKS + ((cbase + key - 4) * 2 + kvh) * 64 + d4); vv = *(const f32x4*)(P.out + O_WVS + ((cbase + key - 4) * 2 + kvh) * 64 + d4); }
;             Ks[key * 65 + d4] = kv[0]; Ks[key * 65 + d4 + 1] = kv[1]; Ks[key * 65 + d4 + 2] = kv[2]; Ks[key * 65 + d4 + 3] = kv[3];
;             *(LAS f32x4*)(Vs + key * 64 + d4) = vv;
;             if (key >= 4 && key < 128) { *(f32x4*)(P.out + O_WKS + ((cbase + key - 4) * 2 + kvh) * 64 + d4) = kv; *(f32x4*)(P.out + O_WVS + ((cbase + key - 4) * 2 + kvh) * 64 + d4) = vv; }
;         }
;     }
;     for (int e = tid; e < 16 * 64; e += 512) {
;         const int row = e >> 6, d = e & 63, g = row >> 2, s = row & 3, p = d < 32 ? 2 * d : 2 * (d - 32) + 1;
;         qs[e] = bf2f(Q[(size_t)(NPT + db * 4 + s) * 512 + (kvh * 4 + g) * 64 + p]);
;     }
.LBB0_954:
	s_cmpk_gt_i32 s14, 0x203
	s_mov_b64 s[0:1], -1
	s_cbranch_scc0 .LBB0_1019
	s_add_i32 s0, s14, 0xfffffdfc
	v_mov_b32_e32 v8, v216
	s_lshr_b32 s16, s0, 1
	s_and_b32 s15, s14, 1
	s_add_i32 s68, s16, s12
	s_movk_i32 s0, 0x840
	v_cmp_gt_i32_e32 vcc, s0, v8
	s_lshl_b32 s4, s68, 7
	v_lshlrev_b32_e32 v11, 2, v8
	v_and_b32_e32 v9, 60, v11
	v_lshlrev_b32_e32 v10, 2, v9
	v_lshrrev_b32_e32 v12, 4, v8
	v_add_u32_e32 v14, s4, v12
	v_lshlrev_b32_e32 v14, 9, v14
	s_lshl_b32 s5, s15, 8
	v_add3_u32 v14, v14, s5, v10
	v_mov_b32_e32 v15, 0
	v_readlane_b32 s40, v252, 29
	v_readlane_b32 s41, v252, 30
	v_readlane_b32 s42, v252, 31
	v_readlane_b32 s43, v252, 32
	v_readlane_b32 s44, v254, 10
	v_readlane_b32 s45, v254, 11
	v_readlane_b32 s46, v254, 14
	v_readlane_b32 s47, v254, 15
	s_mov_b64 s[2:3], 0x4000
	v_readfirstlane_b32 s17, v8
	s_nop 1
	v_lshl_add_u64 v[16:17], s[40:41], 0, v[14:15]
	v_lshl_add_u64 v[26:27], s[42:43], 0, v[14:15]
	global_load_dwordx4 v[48:51], v[16:17], off
	global_load_dwordx4 v[68:71], v[26:27], off
	v_lshl_add_u64 v[18:19], v[16:17], 0, s[2:3]
	v_lshl_add_u64 v[28:29], v[26:27], 0, s[2:3]
	global_load_dwordx4 v[52:55], v[18:19], off
	global_load_dwordx4 v[72:75], v[28:29], off
	v_lshl_add_u64 v[20:21], v[18:19], 0, s[2:3]
	v_lshl_add_u64 v[30:31], v[28:29], 0, s[2:3]
	global_load_dwordx4 v[56:59], v[20:21], off
	global_load_dwordx4 v[76:79], v[30:31], off
	v_lshl_add_u64 v[22:23], v[20:21], 0, s[2:3]
	v_lshl_add_u64 v[32:33], v[30:31], 0, s[2:3]
	global_load_dwordx4 v[60:63], v[22:23], off
	global_load_dwordx4 v[84:87], v[32:33], off
	v_lshl_add_u64 v[16:17], s[44:45], 0, v[14:15]
	v_lshl_add_u64 v[26:27], s[46:47], 0, v[14:15]
	s_cmp_lt_u32 s17, 64
	s_cbranch_scc0 .Lsa_no_k4
	s_mov_b64 s[8:9], 0x10000
	v_lshl_add_u64 v[24:25], v[16:17], 0, s[8:9]
	v_lshl_add_u64 v[34:35], v[26:27], 0, s[8:9]
	global_load_dwordx4 v[64:67], v[24:25], off offset:-2048
	global_load_dwordx4 v[88:91], v[34:35], off offset:-2048
.Lsa_no_k4:
	v_mul_u32_u24_e32 v36, 0x104, v12
	v_add_u32_e32 v36, v36, v10
	v_lshl_add_u32 v37, v12, 8, v10
	v_add_u32_e32 v38, 0x2080, v36
	v_add_u32_e32 v39, 0x4100, v36
	v_add_u32_e32 v13, 0x6180, v36
	s_waitcnt vmcnt(0)
	ds_write2_b32 v36, v48, v49 offset1:1
	ds_write2_b32 v36, v50, v51 offset0:2 offset1:3
	ds_write_b128 v37, v[68:71] offset:34320
	ds_write2_b32 v38, v52, v53 offset1:1
	ds_write2_b32 v38, v54, v55 offset0:2 offset1:3
	ds_write_b128 v37, v[72:75] offset:42512
	ds_write2_b32 v39, v56, v57 offset1:1
	ds_write2_b32 v39, v58, v59 offset0:2 offset1:3
	ds_write_b128 v37, v[76:79] offset:50704
	ds_write2_b32 v13, v60, v61 offset1:1
	ds_write2_b32 v13, v62, v63 offset0:2 offset1:3
	ds_write_b128 v37, v[84:87] offset:58896
	s_cmp_lt_u32 s17, 64
	s_cbranch_scc1 .Lsa_k0_nostore
	global_store_dwordx4 v[16:17], v[48:51], off offset:-2048
	global_store_dwordx4 v[26:27], v[68:71], off offset:-2048
.Lsa_k0_nostore:
	v_lshl_add_u64 v[18:19], v[16:17], 0, s[2:3]
	v_lshl_add_u64 v[28:29], v[26:27], 0, s[2:3]
	global_store_dwordx4 v[18:19], v[52:55], off offset:-2048
	global_store_dwordx4 v[28:29], v[72:75], off offset:-2048
	v_lshl_add_u64 v[20:21], v[18:19], 0, s[2:3]
	v_lshl_add_u64 v[30:31], v[28:29], 0, s[2:3]
	global_store_dwordx4 v[20:21], v[56:59], off offset:-2048
	global_store_dwordx4 v[30:31], v[76:79], off offset:-2048
	v_lshl_add_u64 v[22:23], v[20:21], 0, s[2:3]
	v_lshl_add_u64 v[32:33], v[30:31], 0, s[2:3]
	global_store_dwordx4 v[22:23], v[60:63], off offset:-2048
	global_store_dwordx4 v[32:33], v[84:87], off offset:-2048
	s_cmp_lt_u32 s17, 64
	s_cbranch_scc0 .Lsa_done
	v_add_u32_e32 v38, 0x8200, v36
	v_add_u32_e32 v39, 0x8000, v37
	ds_write2_b32 v38, v64, v65 offset1:1
	ds_write2_b32 v38, v66, v67 offset0:2 offset1:3
	ds_write_b128 v39, v[88:91] offset:34320
.Lsa_done:
	s_mov_b64 s[0:1], exec
.LBB0_990:
	s_or_b64 exec, exec, s[0:1]
	s_movk_i32 s0, 0x400
	v_and_b32_e32 v0, 63, v8
	v_cmp_gt_i32_e64 s[36:37], s0, v8
	s_and_saveexec_b64 s[2:3], s[36:37]
	s_cbranch_execz .LBB0_1000
	v_lshlrev_b32_e32 v1, 1, v0
	v_subrev_u32_e32 v2, 63, v1
	v_cmp_gt_u32_e64 s[38:39], 32, v0
	s_lshl_b32 s0, s16, 2
	s_add_i32 s17, s0, 0x4080
	v_cndmask_b32_e64 v2, v2, v1, s[38:39]
	v_max_i32_e32 v1, 0x200, v8
	v_sub_u32_e32 v1, v1, v8
	v_add_u32_e32 v1, 0x1ff, v1
	s_lshl_b32 s18, s15, 8
	v_mov_b32_e32 v3, v81
	v_cmp_lt_u32_e64 s[38:39], s56, v1
	s_mov_b64 s[0:1], -1
	v_mov_b32_e32 v4, v8
	s_and_saveexec_b64 s[4:5], s[38:39]
	s_cbranch_execz .LBB0_997
	v_lshrrev_b32_e32 v1, 9, v1
	v_readlane_b32 s40, v252, 1
	v_add_u32_e32 v6, 1, v1
	v_readlane_b32 s41, v252, 2
	v_and_b32_e32 v1, 0xfffffe, v6
	v_add_u32_e32 v9, 0x200, v8
	v_readlane_b32 s8, v255, 63
	v_readlane_b32 s42, v252, 3
	v_readlane_b32 s43, v252, 4
	v_readlane_b32 s44, v252, 5
	v_readlane_b32 s45, v252, 6
	v_readlane_b32 s46, v252, 7
	s_mov_b64 s[24:25], s[40:41]
	s_mov_b32 s0, s17
	s_mov_b32 s1, s18
	v_add_u32_e32 v7, s8, v11
	s_mov_b64 s[8:9], 0
	v_mov_b32_e32 v10, v1
	v_mov_b64_e32 v[4:5], v[8:9]
	s_mov_b64 s[26:27], s[42:43]
	v_readlane_b32 s47, v252, 8
	s_mov_b64 s[28:29], s[44:45]
	s_mov_b32 s30, s46
